# retstate: unit index permuted so the 4 units sharing a (batch,head) K/V stream run on one XCD (L2 reuse); norm prologue shift loads hoisted
# baseline (speedup 1.0000x reference)
.LBB0_388:
	v_ashrrev_i32_e32 v21, 31, v13
	v_mov_b32_e32 v20, v13
	v_ashrrev_i32_e32 v23, 31, v12
	v_mov_b32_e32 v22, v12
	v_lshlrev_b64 v[22:23], 2, v[22:23]
	v_lshlrev_b64 v[20:21], 2, v[20:21]
	v_lshl_add_u64 v[24:25], s[52:53], 0, v[22:23]
	v_lshl_add_u64 v[26:27], s[52:53], 0, v[20:21]
	global_load_dword v24, v[24:25], off
	s_nop 0
	global_load_dword v25, v[26:27], off
	v_lshl_add_u64 v[26:27], s[86:87], 0, v[22:23]
	v_lshl_add_u64 v[28:29], s[86:87], 0, v[20:21]
	global_load_dword v26, v[26:27], off
	s_nop 0
	global_load_dword v27, v[28:29], off
	v_lshl_add_u64 v[22:23], s[94:95], 0, v[22:23]
	v_lshl_add_u64 v[20:21], s[94:95], 0, v[20:21]
	global_load_dword v19, v[22:23], off
	s_nop 0
	global_load_dword v20, v[20:21], off
	v_add_u32_e32 v1, -1, v1
	v_cmp_eq_u32_e32 vcc, 0, v1
	v_add_u32_e32 v13, 0x400, v13
	v_add_u32_e32 v12, 0x400, v12
	s_or_b64 s[58:59], vcc, s[58:59]
	s_waitcnt vmcnt(0)
	v_pk_add_f32 v[26:27], v[26:27], 1.0 op_sel_hi:[1,0]
	s_nop 0
	v_pk_mul_f32 v[24:25], v[24:25], v[26:27]
	ds_write2st64_b32 v15, v24, v25 offset1:8
	ds_write2st64_b32 v15, v19, v20 offset0:32 offset1:40
	v_add_u32_e32 v15, 0x1000, v15
	s_andn2_b64 exec, exec, s[58:59]
	s_cbranch_execnz .LBB0_388

.LBB0_707:
	v_readlane_b32 s6, v254, 23
	v_readlane_b32 s7, v254, 24
	s_mov_b64 s[0:1], s[50:51]
	v_mov_b32_e32 v0, v210
	v_cndmask_b32_e64 v1, 0, 1, s[6:7]
	v_cmp_ne_u32_e64 s[4:5], 1, v1
	s_andn2_b64 vcc, exec, s[6:7]
	s_mov_b32 s11, 0x3f2aaaab
	s_mov_b32 s12, 0x3f317218
	s_cbranch_vccnz .LBB0_716
	v_lshlrev_b32_e32 v1, 3, v0
	v_ashrrev_i32_e32 v100, 3, v0
	s_movk_i32 s6, 0xffe0
	v_ashrrev_i32_e32 v98, 4, v0
	v_and_b32_e32 v2, 56, v1
	s_waitcnt lgkmcnt(0)
	v_and_b32_e32 v4, 0x78, v1
	v_and_b32_e32 v1, 16, v0
	v_bfe_u32 v3, v0, 2, 2
	v_bfe_u32 v5, v0, 5, 1
	v_bfi_b32 v118, s6, v100, v0
	v_lshrrev_b32_e32 v6, 1, v0
	v_lshlrev_b32_e32 v0, 2, v0
	v_and_b32_e32 v7, 0xffffffe0, v100
	v_and_b32_e32 v6, 0x60, v6
	v_lshl_or_b32 v3, v5, 3, v3
	v_and_b32_e32 v0, 12, v0
	s_add_u32 s8, s0, 0xd5d0000
	v_lshlrev_b32_e32 v8, 2, v5
	v_mul_u32_u24_e32 v3, 0x88, v3
	v_or3_b32 v5, v1, v6, v0
	v_or3_b32 v0, v1, v7, v0
	s_addc_u32 s9, s1, 0
	v_add_lshl_u32 v0, v0, v3, 1
	s_add_i32 s6, 0, 0x8800
	v_add_u32_e32 v120, s6, v0
	s_movk_i32 s6, 0x88
	v_mul_lo_u32 v1, v98, s6
	v_add_lshl_u32 v5, v5, v3, 1
	v_add_lshl_u32 v130, v1, v4, 1
	v_mul_lo_u32 v1, v100, s6
	s_add_i32 s6, 0, 0x4400
	v_add_u32_e32 v134, s6, v5
	v_readlane_b32 s6, v255, 26
	v_add_lshl_u32 v1, v1, v2, 1
	v_ashrrev_i32_e32 v99, 31, v98
	v_add_u32_e32 v135, s6, v0
	v_readlane_b32 s6, v255, 27
	v_ashrrev_i32_e32 v101, 31, v100
	v_add_u32_e32 v119, 0, v5
	v_add_u32_e32 v136, s6, v5
	v_readlane_b32 s6, v255, 28
	v_add_u32_e32 v121, s92, v5
	v_add_u32_e32 v122, s22, v0
	v_sub_u32_e32 v123, 0x7f, v98
	v_add_u32_e32 v124, 32, v98
	v_sub_u32_e32 v125, 0x5f, v98
	v_add_u32_e32 v126, 64, v98
	v_sub_u32_e32 v127, 63, v98
	v_add_u32_e32 v128, 0x60, v98
	v_sub_u32_e32 v129, 31, v98
	v_add_u32_e32 v131, 0x2200, v130
	v_add_u32_e32 v132, 0x4400, v130
	v_add_u32_e32 v133, 0x6600, v130
	v_add_u32_e32 v137, s6, v0
	v_lshlrev_b32_e32 v32, 1, v4
	v_lshlrev_b32_e32 v102, 1, v2
	v_lshlrev_b32_e32 v104, 1, v6
	v_lshlrev_b32_e32 v106, 1, v8
	v_add_u32_e32 v138, 0, v1
	s_lshr_b32 s14, s26, 5
	s_lshl_b32 s14, s14, 3
	s_and_b32 s15, s26, 7
	s_or_b32 s14, s14, s15
	s_lshl_b32 s14, s14, 2
	s_bfe_u32 s15, s26, 0x20003
	s_or_b32 s14, s14, s15
	s_branch .LBB0_710
